# attention: one static s_setprio 1 for the second (staggered) half-workgroup during the phase
# baseline (speedup 1.0000x reference)
; __device__ __forceinline__ void phase_attn(const PT& p, LAS unsigned char* lds, int tid, int lane, int wave) {
;     ...
;     for (int u = blockIdx.x; u < NBATCH * 16 * 8; u += gridDim.x) {
;         const int j = u & 7, hd = (u >> 3) & 15, b = u >> 7;
; #pragma unroll 1
;         for (int k = 0; k < 2; ++k) attn_unit(p, lds, tid, lane, wave, b, hd, k == 0 ? 15 - j : j, lam);
.LBB0_1072:
	s_and_b64 vcc, exec, s[58:59]
	s_cbranch_vccz .Lprio_skip
	s_setprio 1

; __device__ __forceinline__ unsigned xb_ld(unsigned* p)              { return __hip_atomic_load(p, __ATOMIC_RELAXED, __HIP_MEMORY_SCOPE_AGENT); }
; __device__ __forceinline__ void xcd_barrier_complete(unsigned* bar, unsigned x, unsigned& nloc, unsigned& nx) {
;     const unsigned G = gridDim.x * gridDim.y * gridDim.z;
;     unsigned sum, cnt, mine, sp = 0u;
;     for (;;) {
;         sum = 0u; cnt = 0u; mine = 0u;
; #pragma unroll
;         for (unsigned j = 0; j < 16; ++j) { const unsigned c = xb_ld(&bar[XB_XCNT(j)]); sum += c; cnt += (c > 0u) ? 1u : 0u; mine = (j == x) ? c : mine; }
; __device__ __forceinline__ void xcd_barrier(const XcdBarrier& b) {
;     asm volatile("s_waitcnt vmcnt(0)" ::: "memory");
;     __syncthreads();
;     if (threadIdx.x == 0) {
;         unsigned* bar = b.bar;
;         __builtin_amdgcn_s_waitcnt(0);
;         unsigned nloc = b.st[0], nx = b.st[1];
;         if (nloc == 0u) { xcd_barrier_complete(bar, b.x, nloc, nx); b.st[0] = nloc; b.st[1] = nx; }
.LBB0_1111:
	s_setprio 0
	s_waitcnt vmcnt(0)
	s_waitcnt lgkmcnt(0)
	s_barrier
	s_and_saveexec_b64 s[0:1], s[92:93]
	s_cbranch_execz .LBB0_1163
	s_add_i32 s2, 0, 0x23f00
	v_mov_b32_e32 v0, s2
	s_waitcnt vmcnt(0) expcnt(0) lgkmcnt(0)
	ds_read_b32 v2, v0
	s_add_i32 s2, 0, 0x23f04
	v_mov_b32_e32 v0, s2
	ds_read_b32 v0, v0
	s_waitcnt lgkmcnt(1)
	v_cmp_ne_u32_e32 vcc, 0, v2
	s_cbranch_vccnz .LBB0_1127
	v_readlane_b32 s2, v249, 0
	v_readlane_b32 s3, v249, 1
	s_mul_i32 s33, s3, s89
	s_mul_i32 s33, s33, s2
	s_add_u32 s2, s84, 0x60200
	s_addc_u32 s3, s85, 0
	s_add_u32 s4, s84, 0x60400
	s_addc_u32 s5, s85, 0
	s_add_u32 s6, s84, 0x60500
	s_addc_u32 s7, s85, 0
	s_add_u32 s8, s84, 0x60600
	s_addc_u32 s9, s85, 0
	s_add_u32 s10, s84, 0x60700
	s_addc_u32 s11, s85, 0
	s_add_u32 s12, s84, 0x60800
	s_addc_u32 s13, s85, 0
	s_add_u32 s14, s84, 0x60900
	s_addc_u32 s15, s85, 0
	s_add_u32 s16, s84, 0x60a00
	s_addc_u32 s17, s85, 0
	s_add_u32 s18, s84, 0x60b00
	s_addc_u32 s19, s85, 0
	s_add_u32 s20, s84, 0x60c00
	s_addc_u32 s21, s85, 0
	s_add_u32 s22, s84, 0x60d00
	s_addc_u32 s23, s85, 0
	s_add_u32 s24, s84, 0x60e00
	s_addc_u32 s25, s85, 0
	s_add_u32 s26, s84, 0x60f00
	s_addc_u32 s27, s85, 0
	s_add_u32 s28, s84, 0x61000
	s_addc_u32 s29, s85, 0
	s_add_u32 s30, s84, 0x61100
	s_addc_u32 s31, s85, 0
	s_add_u32 s34, s84, 0x61200
	s_addc_u32 s35, s85, 0
	s_add_u32 s36, s84, 0x61300
	s_addc_u32 s37, s85, 0
	s_mov_b32 s38, 1
	v_mov_b32_e32 v16, 0
	s_branch .LBB0_1115
